# grid barrier: acquire invalidate issued with the arrival atomic by every workgroup; followers poll the top-level generation word; leader late invalidate dropped
# speedup vs baseline: 1.0232x; 1.0032x over previous
.LBB0_86:
	s_mov_b64 s[12:13], exec
	s_lshl_b32 s10, s3, 8
	v_readlane_b32 s14, v240, 2
	v_mbcnt_lo_u32_b32 v3, s12, 0
	v_readlane_b32 s15, v240, 3
	s_add_u32 s10, s14, s10
	v_mbcnt_hi_u32_b32 v3, s13, v3
	s_addc_u32 s11, s15, 0
	v_cmp_eq_u32_e32 vcc, 0, v3
	s_and_saveexec_b64 s[14:15], vcc
	s_cbranch_execz .LBB0_88
	s_bcnt1_i32_b64 s12, s[12:13]
	v_mov_b32_e32 v5, 0x1000
	v_mov_b32_e32 v6, s12
	global_atomic_add v5, v5, v6, s[10:11] offset:1024 sc0
	buffer_inv sc1
.LBB0_88:
	s_or_b64 exec, exec, s[14:15]
	v_cvt_f32_u32_e32 v6, v4
	s_waitcnt vmcnt(0)
	v_readfirstlane_b32 s12, v5
	v_sub_u32_e32 v5, 0, v4
	v_rcp_iflag_f32_e32 v6, v6
	v_add_u32_e32 v7, s12, v3
	v_mul_f32_e32 v6, 0x4f7ffffe, v6
	v_cvt_u32_f32_e32 v6, v6
	v_mul_lo_u32 v3, v5, v6
	v_mul_hi_u32 v3, v6, v3
	v_add_u32_e32 v3, v6, v3
	v_mul_hi_u32 v3, v7, v3
	v_mul_lo_u32 v5, v3, v4
	v_sub_u32_e32 v5, v7, v5
	v_add_u32_e32 v6, 1, v3
	v_cmp_ge_u32_e32 vcc, v5, v4
	s_nop 1
	v_cndmask_b32_e32 v3, v3, v6, vcc
	v_sub_u32_e32 v6, v5, v4
	v_cndmask_b32_e32 v5, v5, v6, vcc
	v_add_u32_e32 v6, 1, v3
	v_cmp_ge_u32_e32 vcc, v5, v4
	v_add_u32_e32 v5, 1, v7
	s_nop 0
	v_cndmask_b32_e32 v3, v3, v6, vcc
	v_mul_lo_u32 v6, v4, v3
	v_add_u32_e32 v4, v6, v4
	v_cmp_ne_u32_e32 vcc, v5, v4
	s_and_saveexec_b64 s[12:13], vcc
	s_xor_b64 s[12:13], exec, s[12:13]
	s_cbranch_execz .LBB0_102
	s_waitcnt lgkmcnt(0)
	v_mov_b32_e32 v2, 0
	s_add_u32 s18, s66, 0x1bc3500
	s_addc_u32 s19, s67, 0
	global_load_dword v2, v2, s[18:19] sc1
	s_waitcnt vmcnt(0)
	v_cmp_eq_u32_e32 vcc, v2, v3
	s_and_saveexec_b64 s[14:15], vcc
	s_cbranch_execz .LBB0_101
	s_add_u32 s16, s66, 0x1bc0200
	s_addc_u32 s17, s67, 0
	s_mov_b32 s30, 1
	s_mov_b64 s[20:21], 0
	v_mov_b32_e32 v2, 0
	s_branch .LBB0_92

.LBB0_243:
	s_mov_b64 s[12:13], exec
	s_lshl_b32 s10, s3, 8
	v_readlane_b32 s0, v240, 2
	v_mbcnt_lo_u32_b32 v3, s12, 0
	v_readlane_b32 s1, v240, 3
	s_add_u32 s10, s0, s10
	v_mbcnt_hi_u32_b32 v3, s13, v3
	s_addc_u32 s11, s1, 0
	v_cmp_eq_u32_e32 vcc, 0, v3
	s_and_saveexec_b64 s[14:15], vcc
	s_cbranch_execz .LBB0_245
	s_bcnt1_i32_b64 s12, s[12:13]
	v_mov_b32_e32 v5, 0x1000
	v_mov_b32_e32 v6, s12
	global_atomic_add v5, v5, v6, s[10:11] offset:1024 sc0
	buffer_inv sc1

.LBB0_528:
	s_mov_b64 s[10:11], exec
	s_lshl_b32 s8, s3, 8
	v_readlane_b32 s0, v240, 2
	v_mbcnt_lo_u32_b32 v3, s10, 0
	v_readlane_b32 s1, v240, 3
	s_add_u32 s8, s0, s8
	v_mbcnt_hi_u32_b32 v3, s11, v3
	s_addc_u32 s9, s1, 0
	v_cmp_eq_u32_e32 vcc, 0, v3
	s_and_saveexec_b64 s[12:13], vcc
	s_cbranch_execz .LBB0_530
	s_bcnt1_i32_b64 s10, s[10:11]
	v_mov_b32_e32 v5, 0x1000
	v_mov_b32_e32 v6, s10
	global_atomic_add v5, v5, v6, s[8:9] offset:1024 sc0
	buffer_inv sc1
.LBB0_530:
	s_or_b64 exec, exec, s[12:13]
	v_cvt_f32_u32_e32 v6, v4
	s_waitcnt vmcnt(0)
	v_readfirstlane_b32 s10, v5
	v_sub_u32_e32 v5, 0, v4
	v_rcp_iflag_f32_e32 v6, v6
	v_add_u32_e32 v7, s10, v3
	v_mul_f32_e32 v6, 0x4f7ffffe, v6
	v_cvt_u32_f32_e32 v6, v6
	v_mul_lo_u32 v3, v5, v6
	v_mul_hi_u32 v3, v6, v3
	v_add_u32_e32 v3, v6, v3
	v_mul_hi_u32 v3, v7, v3
	v_mul_lo_u32 v5, v3, v4
	v_sub_u32_e32 v5, v7, v5
	v_add_u32_e32 v6, 1, v3
	v_cmp_ge_u32_e32 vcc, v5, v4
	s_nop 1
	v_cndmask_b32_e32 v3, v3, v6, vcc
	v_sub_u32_e32 v6, v5, v4
	v_cndmask_b32_e32 v5, v5, v6, vcc
	v_add_u32_e32 v6, 1, v3
	v_cmp_ge_u32_e32 vcc, v5, v4
	v_add_u32_e32 v5, 1, v7
	s_nop 0
	v_cndmask_b32_e32 v3, v3, v6, vcc
	v_mul_lo_u32 v6, v4, v3
	v_add_u32_e32 v4, v6, v4
	v_cmp_ne_u32_e32 vcc, v5, v4
	s_and_saveexec_b64 s[10:11], vcc
	s_xor_b64 s[10:11], exec, s[10:11]
	s_cbranch_execz .LBB0_544
	s_waitcnt lgkmcnt(0)
	v_mov_b32_e32 v2, 0
	s_add_u32 s16, s66, 0x1bc3500
	s_addc_u32 s17, s67, 0
	global_load_dword v2, v2, s[16:17] sc1
	s_waitcnt vmcnt(0)
	v_cmp_eq_u32_e32 vcc, v2, v3
	s_and_saveexec_b64 s[12:13], vcc
	s_cbranch_execz .LBB0_543
	s_add_u32 s14, s66, 0x1bc0200
	s_addc_u32 s15, s67, 0
	s_mov_b32 s28, 1
	s_mov_b64 s[18:19], 0
	v_mov_b32_e32 v2, 0
	s_branch .LBB0_534

.LBB0_647:
	s_mov_b64 s[10:11], exec
	s_lshl_b32 s8, s3, 8
	v_readlane_b32 s12, v240, 2
	v_mbcnt_lo_u32_b32 v3, s10, 0
	v_readlane_b32 s13, v240, 3
	s_add_u32 s8, s12, s8
	v_mbcnt_hi_u32_b32 v3, s11, v3
	s_addc_u32 s9, s13, 0
	v_cmp_eq_u32_e32 vcc, 0, v3
	s_and_saveexec_b64 s[12:13], vcc
	s_cbranch_execz .LBB0_649
	s_bcnt1_i32_b64 s10, s[10:11]
	v_mov_b32_e32 v5, 0x1000
	v_mov_b32_e32 v6, s10
	global_atomic_add v5, v5, v6, s[8:9] offset:1024 sc0
	buffer_inv sc1

.LBB0_772:
	s_mov_b64 s[10:11], exec
	s_lshl_b32 s8, s3, 8
	v_mbcnt_lo_u32_b32 v3, s10, 0
	s_add_u32 s8, s72, s8
	v_mbcnt_hi_u32_b32 v3, s11, v3
	s_addc_u32 s9, s73, 0
	v_cmp_eq_u32_e32 vcc, 0, v3
	s_and_saveexec_b64 s[12:13], vcc
	s_cbranch_execz .LBB0_774
	s_bcnt1_i32_b64 s10, s[10:11]
	v_mov_b32_e32 v5, 0x1000
	v_mov_b32_e32 v6, s10
	global_atomic_add v5, v5, v6, s[8:9] offset:1024 sc0
	buffer_inv sc1

.LBB0_1566:
	s_mov_b64 s[10:11], exec
	s_lshl_b32 s3, s3, 8
	v_mbcnt_lo_u32_b32 v3, s10, 0
	s_add_u32 s8, s72, s3
	v_mbcnt_hi_u32_b32 v3, s11, v3
	s_addc_u32 s9, s73, 0
	v_cmp_eq_u32_e32 vcc, 0, v3
	s_and_saveexec_b64 s[12:13], vcc
	s_cbranch_execz .LBB0_1568
	s_bcnt1_i32_b64 s3, s[10:11]
	v_mov_b32_e32 v5, 0x1000
	v_mov_b32_e32 v6, s3
	global_atomic_add v5, v5, v6, s[8:9] offset:1024 sc0
	buffer_inv sc1
.LBB0_1568:
	s_or_b64 exec, exec, s[12:13]
	v_cvt_f32_u32_e32 v6, v4
	s_waitcnt vmcnt(0)
	v_readfirstlane_b32 s3, v5
	v_sub_u32_e32 v5, 0, v4
	v_rcp_iflag_f32_e32 v6, v6
	v_add_u32_e32 v7, s3, v3
	v_mul_f32_e32 v6, 0x4f7ffffe, v6
	v_cvt_u32_f32_e32 v6, v6
	v_mul_lo_u32 v3, v5, v6
	v_mul_hi_u32 v3, v6, v3
	v_add_u32_e32 v3, v6, v3
	v_mul_hi_u32 v3, v7, v3
	v_mul_lo_u32 v5, v3, v4
	v_sub_u32_e32 v5, v7, v5
	v_add_u32_e32 v6, 1, v3
	v_cmp_ge_u32_e32 vcc, v5, v4
	s_nop 1
	v_cndmask_b32_e32 v3, v3, v6, vcc
	v_sub_u32_e32 v6, v5, v4
	v_cndmask_b32_e32 v5, v5, v6, vcc
	v_add_u32_e32 v6, 1, v3
	v_cmp_ge_u32_e32 vcc, v5, v4
	v_add_u32_e32 v5, 1, v7
	s_nop 0
	v_cndmask_b32_e32 v3, v3, v6, vcc
	v_mul_lo_u32 v6, v4, v3
	v_add_u32_e32 v4, v6, v4
	v_cmp_ne_u32_e32 vcc, v5, v4
	s_and_saveexec_b64 s[10:11], vcc
	s_xor_b64 s[10:11], exec, s[10:11]
	s_cbranch_execz .LBB0_1582
	s_waitcnt lgkmcnt(0)
	v_mov_b32_e32 v2, 0
	s_add_u32 s16, s66, 0x1bc3500
	s_addc_u32 s17, s67, 0
	global_load_dword v2, v2, s[16:17] sc1
	s_waitcnt vmcnt(0)
	v_cmp_eq_u32_e32 vcc, v2, v3
	s_and_saveexec_b64 s[12:13], vcc
	s_cbranch_execz .LBB0_1581
	s_add_u32 s14, s66, 0x1bc0200
	s_addc_u32 s15, s67, 0
	s_mov_b32 s3, 1
	s_mov_b64 s[18:19], 0
	v_mov_b32_e32 v2, 0
	s_branch .LBB0_1572
